# v4 + P8 sample-row mini GEMM: second k-pair's 20 loads hoisted to issue with the first (fresh registers) instead of load/vmcnt(1) ladder
# speedup vs baseline: 1.0012x; 1.0012x over previous
;     ...
;     for (int u = (int)((blockIdx.x + rot) % G); u < n_rb * NSUB * ncu; u += G) {
;         const int cu = u % ncu, t_ = u / ncu, rowb = row0 + (t_ / NSUB) * 128 + (t_ % NSUB) * (16 * NRB);
;         const bf16* ap = A + (size_t)(rowb + l15) * K + wave * (K >> 3) + quad * 8;
;         const int brow = TWO ? ((16 * cu) >> 7) * 256 + ((16 * cu) & 127) : 16 * cu;
;         const bf16* bp = Bt + (size_t)(brow + l15) * K + wave * (K >> 3) + quad * 8;
;         f32x4 acc0[NRB], acc1[NRB];
; #pragma unroll
;         for (int r = 0; r < NRB; ++r) { acc0[r] = (f32x4){0.f, 0.f, 0.f, 0.f}; acc1[r] = (f32x4){0.f, 0.f, 0.f, 0.f}; }
;         constexpr int KS = TWO ? 2 : (NRB == 8 ? 4 : 12);
;         for (int s0 = 0; s0 < nsw; s0 += KS) {
;             bf16x8 a[KS][NRB], b[KS], c[KS];
; #pragma unroll
;             for (int s = 0; s < KS; ++s) { const bool on = s0 + s < nsw; const int ko = (s0 + s) * 32;
;                 b[s] = on ? *(const bf16x8*)(bp + ko) : (bf16x8){0, 0, 0, 0, 0, 0, 0, 0}; if (TWO) c[s] = on ? *(const bf16x8*)(bp + (size_t)128 * K + ko) : (bf16x8){0, 0, 0, 0, 0, 0, 0, 0};
; #pragma unroll
;                 for (int r = 0; r < NRB; ++r) a[s][r] = on ? *(const bf16x8*)(ap + (size_t)(16 * r) * K + ko) : (bf16x8){0, 0, 0, 0, 0, 0, 0, 0}; }
; #pragma unroll
;             for (int s = 0; s < KS; ++s)
; #pragma unroll
;                 for (int r = 0; r < NRB; ++r) { acc0[r] = __builtin_amdgcn_mfma_f32_16x16x32_bf16(b[s], a[s][r], acc0[r], 0, 0, 0); if (TWO) acc1[r] = __builtin_amdgcn_mfma_f32_16x16x32_bf16(c[s], a[s][r], acc1[r], 0, 0, 0); }
.LBB0_985:
	s_mul_hi_i32 s0, s3, 0x2e8ba2e9
	s_lshr_b32 s1, s0, 31
	s_ashr_i32 s0, s0, 5
	s_add_i32 s0, s0, s1
	s_lshl_b32 s26, s0, 7
	s_addk_i32 s26, 0x4000
	v_or_b32_e32 v4, s26, v145
	s_mul_i32 s1, s0, 0xfffff500
	s_mulk_i32 s0, 0xea00
	s_add_i32 s27, s6, s1
	s_add_i32 s0, s9, s0
	v_ashrrev_i32_e32 v5, 31, v4
	s_and_b32 s0, s0, 0xffffff00
	s_and_b32 s1, s27, 0x70
	v_lshlrev_b64 v[4:5], 11, v[4:5]
	s_or_b32 s0, s0, s1
	v_lshl_add_u64 v[118:119], v[32:33], 0, v[4:5]
	v_or_b32_e32 v0, s0, v145
	v_add_co_u32_e64 v120, s[0:1], s18, v118
	v_ashrrev_i32_e32 v1, 31, v0
	s_nop 0
	v_addc_co_u32_e64 v121, s[0:1], 0, v119, s[0:1]
	v_add_co_u32_e64 v122, s[0:1], s19, v118
	v_lshlrev_b64 v[0:1], 11, v[0:1]
	s_nop 0
	v_addc_co_u32_e64 v123, s[0:1], 0, v119, s[0:1]
	v_add_co_u32_e64 v124, s[0:1], s20, v118
	v_lshl_add_u64 v[116:117], v[34:35], 0, v[0:1]
	s_nop 0
	v_addc_co_u32_e64 v125, s[0:1], 0, v119, s[0:1]
	v_add_co_u32_e64 v126, s[0:1], s21, v118
	global_load_dwordx4 v[0:3], v[116:117], off
	global_load_dwordx4 v[4:7], v[118:119], off
	v_addc_co_u32_e64 v127, s[0:1], 0, v119, s[0:1]
	v_add_co_u32_e64 v128, s[0:1], s22, v118
	global_load_dwordx4 v[8:11], v[120:121], off
	global_load_dwordx4 v[12:15], v[122:123], off
	v_addc_co_u32_e64 v129, s[0:1], 0, v119, s[0:1]
	v_add_co_u32_e64 v130, s[0:1], s23, v118
	global_load_dwordx4 v[16:19], v[124:125], off
	s_nop 0
	v_addc_co_u32_e64 v131, s[0:1], 0, v119, s[0:1]
	v_add_co_u32_e64 v132, s[0:1], s24, v118
	global_load_dwordx4 v[20:23], v[126:127], off
	global_load_dwordx4 v[24:27], v[118:119], off offset:64
	global_load_dwordx4 v[28:31], v[116:117], off offset:64
	v_addc_co_u32_e64 v133, s[0:1], 0, v119, s[0:1]
	v_add_co_u32_e64 v134, s[0:1], s11, v116
	global_load_dwordx4 v[44:47], v[128:129], off
	global_load_dwordx4 v[48:51], v[120:121], off offset:64
	v_addc_co_u32_e64 v135, s[0:1], 0, v117, s[0:1]
	global_load_dwordx4 v[56:59], v[122:123], off offset:64
	global_load_dwordx4 v[64:67], v[130:131], off
	global_load_dwordx4 v[68:71], v[124:125], off offset:64
	global_load_dwordx4 v[76:79], v[126:127], off offset:64
	global_load_dwordx4 v[84:87], v[132:133], off
	global_load_dwordx4 v[88:91], v[128:129], off offset:64
	global_load_dwordx4 v[92:95], v[130:131], off offset:64
	global_load_dwordx4 v[104:107], v[134:135], off
	global_load_dwordx4 v[108:111], v[132:133], off offset:64
	global_load_dwordx4 v[112:115], v[134:135], off offset:64
	global_load_dwordx4 v[164:167], v[116:117], off offset:128
	global_load_dwordx4 v[168:171], v[118:119], off offset:128
	global_load_dwordx4 v[172:175], v[116:117], off offset:192
	global_load_dwordx4 v[176:179], v[118:119], off offset:192
	global_load_dwordx4 v[180:183], v[134:135], off offset:128
	global_load_dwordx4 v[184:187], v[134:135], off offset:192
	global_load_dwordx4 v[188:191], v[120:121], off offset:128
	global_load_dwordx4 v[192:195], v[120:121], off offset:192
	global_load_dwordx4 v[196:199], v[122:123], off offset:128
	global_load_dwordx4 v[200:203], v[122:123], off offset:192
	global_load_dwordx4 v[204:207], v[124:125], off offset:128
	global_load_dwordx4 v[208:211], v[124:125], off offset:192
	global_load_dwordx4 v[212:215], v[126:127], off offset:128
	global_load_dwordx4 v[216:219], v[126:127], off offset:192
	global_load_dwordx4 v[220:223], v[128:129], off offset:128
	global_load_dwordx4 v[224:227], v[128:129], off offset:192
	global_load_dwordx4 v[228:231], v[130:131], off offset:128
	global_load_dwordx4 v[232:235], v[130:131], off offset:192
	global_load_dwordx4 v[136:139], v[132:133], off offset:128
	global_load_dwordx4 v[140:143], v[132:133], off offset:192
	s_waitcnt vmcnt(20)
	v_mfma_f32_16x16x32_bf16 v[36:39], v[0:3], v[4:7], 0
	v_mfma_f32_16x16x32_bf16 v[52:55], v[0:3], v[8:11], 0
	v_mfma_f32_16x16x32_bf16 v[60:63], v[0:3], v[12:15], 0
	v_mfma_f32_16x16x32_bf16 v[72:75], v[0:3], v[16:19], 0
	v_mfma_f32_16x16x32_bf16 v[80:83], v[0:3], v[20:23], 0
	v_mfma_f32_16x16x32_bf16 v[96:99], v[0:3], v[44:47], 0
	v_mfma_f32_16x16x32_bf16 v[100:103], v[0:3], v[64:67], 0
	v_mfma_f32_16x16x32_bf16 v[0:3], v[0:3], v[84:87], 0
	v_mfma_f32_16x16x32_bf16 v[4:7], v[104:107], v[4:7], 0
	v_mfma_f32_16x16x32_bf16 v[8:11], v[104:107], v[8:11], 0
	v_mfma_f32_16x16x32_bf16 v[36:39], v[28:31], v[24:27], v[36:39]
	v_mfma_f32_16x16x32_bf16 v[52:55], v[28:31], v[48:51], v[52:55]
	v_mfma_f32_16x16x32_bf16 v[60:63], v[28:31], v[56:59], v[60:63]
	v_mfma_f32_16x16x32_bf16 v[72:75], v[28:31], v[68:71], v[72:75]
	v_mfma_f32_16x16x32_bf16 v[80:83], v[28:31], v[76:79], v[80:83]
	v_mfma_f32_16x16x32_bf16 v[4:7], v[112:115], v[24:27], v[4:7]
	v_mfma_f32_16x16x32_bf16 v[8:11], v[112:115], v[48:51], v[8:11]
	v_mfma_f32_16x16x32_bf16 v[24:27], v[28:31], v[88:91], v[96:99]
	v_mfma_f32_16x16x32_bf16 v[48:51], v[28:31], v[92:95], v[100:103]
	v_mfma_f32_16x16x32_bf16 v[0:3], v[28:31], v[108:111], v[0:3]
	v_mfma_f32_16x16x32_bf16 v[12:15], v[104:107], v[12:15], 0
	v_mfma_f32_16x16x32_bf16 v[16:19], v[104:107], v[16:19], 0
	v_mfma_f32_16x16x32_bf16 v[20:23], v[104:107], v[20:23], 0
	v_mfma_f32_16x16x32_bf16 v[44:47], v[104:107], v[44:47], 0
	v_mfma_f32_16x16x32_bf16 v[64:67], v[104:107], v[64:67], 0
	v_mfma_f32_16x16x32_bf16 v[84:87], v[104:107], v[84:87], 0
	v_mfma_f32_16x16x32_bf16 v[12:15], v[112:115], v[56:59], v[12:15]
	v_mfma_f32_16x16x32_bf16 v[16:19], v[112:115], v[68:71], v[16:19]
	v_mfma_f32_16x16x32_bf16 v[20:23], v[112:115], v[76:79], v[20:23]
	v_mfma_f32_16x16x32_bf16 v[44:47], v[112:115], v[88:91], v[44:47]
	v_mfma_f32_16x16x32_bf16 v[56:59], v[112:115], v[92:95], v[64:67]
	v_mfma_f32_16x16x32_bf16 v[64:67], v[112:115], v[108:111], v[84:87]
	s_nop 0
	s_waitcnt vmcnt(0)
;     ...
;             for (int s = 0; s < KS; ++s)
; #pragma unroll
;                 for (int r = 0; r < NRB; ++r) { acc0[r] = __builtin_amdgcn_mfma_f32_16x16x32_bf16(b[s], a[s][r], acc0[r], 0, 0, 0); if (TWO) acc1[r] = __builtin_amdgcn_mfma_f32_16x16x32_bf16(c[s], a[s][r], acc1[r], 0, 0, 0); }
;         }
;         f32x4 t0 = (f32x4){0.f, 0.f, 0.f, 0.f}, t1 = (f32x4){0.f, 0.f, 0.f, 0.f};
; #pragma unroll
;         for (int r = 0; r < NRB; ++r) red[(wave * NRB + r) * 64 + lane] = acc0[r];
;         __syncthreads();
;         if (wave < NRB) {
; #pragma unroll
;             for (int s = 0; s < 8; ++s) t0 += red[(s * NRB + wave) * 64 + lane]; }
	v_mfma_f32_16x16x32_bf16 v[36:39], v[164:167], v[168:171], v[36:39]
	v_mfma_f32_16x16x32_bf16 v[4:7], v[180:183], v[168:171], v[4:7]
	v_mfma_f32_16x16x32_bf16 v[52:55], v[164:167], v[188:191], v[52:55]
	v_mfma_f32_16x16x32_bf16 v[8:11], v[180:183], v[188:191], v[8:11]
	v_mfma_f32_16x16x32_bf16 v[60:63], v[164:167], v[196:199], v[60:63]
	v_mfma_f32_16x16x32_bf16 v[12:15], v[180:183], v[196:199], v[12:15]
	v_mfma_f32_16x16x32_bf16 v[72:75], v[164:167], v[204:207], v[72:75]
	v_mfma_f32_16x16x32_bf16 v[16:19], v[180:183], v[204:207], v[16:19]
	v_mfma_f32_16x16x32_bf16 v[80:83], v[164:167], v[212:215], v[80:83]
	v_mfma_f32_16x16x32_bf16 v[20:23], v[180:183], v[212:215], v[20:23]
	v_mfma_f32_16x16x32_bf16 v[24:27], v[164:167], v[220:223], v[24:27]
	v_mfma_f32_16x16x32_bf16 v[44:47], v[180:183], v[220:223], v[44:47]
	v_mfma_f32_16x16x32_bf16 v[48:51], v[164:167], v[228:231], v[48:51]
	v_mfma_f32_16x16x32_bf16 v[56:59], v[180:183], v[228:231], v[56:59]
	v_mfma_f32_16x16x32_bf16 v[28:31], v[164:167], v[136:139], v[0:3]
	v_mfma_f32_16x16x32_bf16 v[64:67], v[180:183], v[136:139], v[64:67]
	v_mfma_f32_16x16x32_bf16 v[36:39], v[172:175], v[176:179], v[36:39]
	v_mfma_f32_16x16x32_bf16 v[0:3], v[184:187], v[176:179], v[4:7]
	v_mfma_f32_16x16x32_bf16 v[4:7], v[184:187], v[192:195], v[8:11]
	v_mfma_f32_16x16x32_bf16 v[60:63], v[172:175], v[200:203], v[60:63]
	v_mfma_f32_16x16x32_bf16 v[8:11], v[184:187], v[200:203], v[12:15]
	v_mfma_f32_16x16x32_bf16 v[12:15], v[184:187], v[208:211], v[16:19]
	v_mfma_f32_16x16x32_bf16 v[16:19], v[184:187], v[216:219], v[20:23]
	v_mfma_f32_16x16x32_bf16 v[20:23], v[172:175], v[224:227], v[24:27]
	v_mfma_f32_16x16x32_bf16 v[52:55], v[172:175], v[192:195], v[52:55]
	ds_write_b128 v43, v[36:39]
	s_nop 6
	ds_write_b128 v43, v[52:55] offset:1024
	v_mfma_f32_16x16x32_bf16 v[72:75], v[172:175], v[208:211], v[72:75]
	v_mov_b32_e32 v38, 0
	v_mov_b32_e32 v39, 0
	v_mov_b32_e32 v36, 0
	v_mfma_f32_16x16x32_bf16 v[24:27], v[172:175], v[232:235], v[48:51]
	v_mov_b32_e32 v37, 0
	v_mfma_f32_16x16x32_bf16 v[80:83], v[172:175], v[216:219], v[80:83]
	ds_write_b128 v43, v[60:63] offset:2048
	s_nop 0
	ds_write_b128 v43, v[72:75] offset:3072
	s_nop 4
	ds_write_b128 v43, v[80:83] offset:4096
	v_mfma_f32_16x16x32_bf16 v[28:31], v[172:175], v[140:143], v[28:31]
	ds_write_b128 v43, v[20:23] offset:5120
	ds_write_b128 v43, v[24:27] offset:6144
	s_nop 5
	ds_write_b128 v43, v[28:31] offset:7168
	s_waitcnt lgkmcnt(0)
	v_mfma_f32_16x16x32_bf16 v[20:23], v[184:187], v[224:227], v[44:47]
	s_barrier
	v_mfma_f32_16x16x32_bf16 v[24:27], v[184:187], v[232:235], v[56:59]
	v_mfma_f32_16x16x32_bf16 v[28:31], v[184:187], v[140:143], v[64:67]
	s_and_saveexec_b64 s[0:1], vcc
	s_cbranch_execz .LBB0_987
	ds_read_b128 v[36:39], v40
	ds_read_b128 v[44:47], v40 offset:8192
	ds_read_b128 v[48:51], v40 offset:16384
	ds_read_b128 v[52:55], v40 offset:24576
	s_waitcnt lgkmcnt(3)
	v_pk_add_f32 v[38:39], v[38:39], 0 op_sel_hi:[1,0]
	v_pk_add_f32 v[36:37], v[36:37], 0 op_sel_hi:[1,0]
	s_waitcnt lgkmcnt(2)
	v_pk_add_f32 v[38:39], v[38:39], v[46:47]
	v_pk_add_f32 v[44:45], v[36:37], v[44:45]
	s_waitcnt lgkmcnt(1)
	v_pk_add_f32 v[46:47], v[38:39], v[50:51]
	ds_read_b128 v[36:39], v40 offset:32768
	v_pk_add_f32 v[44:45], v[44:45], v[48:49]
	s_waitcnt lgkmcnt(1)
	v_pk_add_f32 v[48:49], v[46:47], v[54:55]
	v_pk_add_f32 v[52:53], v[44:45], v[52:53]
	ds_read_b128 v[44:47], v40 offset:40960
	s_waitcnt lgkmcnt(1)
	v_pk_add_f32 v[38:39], v[48:49], v[38:39]
	ds_read_b128 v[48:51], v40 offset:49152
	v_pk_add_f32 v[36:37], v[52:53], v[36:37]
	ds_read_b128 v[52:55], v40 offset:57344
	s_waitcnt lgkmcnt(2)
	v_pk_add_f32 v[38:39], v[38:39], v[46:47]
	v_pk_add_f32 v[36:37], v[36:37], v[44:45]
	s_waitcnt lgkmcnt(1)
	v_pk_add_f32 v[38:39], v[38:39], v[50:51]
	v_pk_add_f32 v[44:45], v[36:37], v[48:49]
	s_waitcnt lgkmcnt(0)
	v_pk_add_f32 v[36:37], v[38:39], v[54:55]
	v_pk_add_f32 v[38:39], v[44:45], v[52:53]
